# grid-barrier spin loops poll without the 64-cycle sleep (s_sleep 0); otherwise v76
# speedup vs baseline: 1.0076x; 1.0076x over previous
.LBB0_95:
	global_load_dword v18, v3, s[84:85] sc1
	global_load_dword v2, v3, s[86:87] sc1
	global_load_dword v4, v3, s[88:89] sc1
	global_load_dword v5, v3, s[90:91] sc1
	global_load_dword v6, v3, s[92:93] sc1
	global_load_dword v7, v3, s[94:95] sc1
	global_load_dword v8, v3, s[96:97] sc1
	global_load_dword v9, v3, s[0:1] sc1
	global_load_dword v10, v3, s[4:5] sc1
	global_load_dword v11, v3, s[6:7] sc1
	global_load_dword v12, v3, s[8:9] sc1
	global_load_dword v13, v3, s[10:11] sc1
	global_load_dword v14, v3, s[12:13] sc1
	global_load_dword v15, v3, s[14:15] sc1
	global_load_dword v16, v3, s[16:17] sc1
	global_load_dword v17, v3, s[20:21] sc1
	s_mov_b64 s[40:41], -1
	s_mov_b64 s[42:43], -1
	s_waitcnt vmcnt(14)
	v_add_u32_e32 v19, v2, v18
	s_waitcnt vmcnt(13)
	v_add_u32_e32 v19, v19, v4
	s_waitcnt vmcnt(12)
	v_add_u32_e32 v19, v19, v5
	s_waitcnt vmcnt(11)
	v_add_u32_e32 v19, v19, v6
	s_waitcnt vmcnt(10)
	v_add_u32_e32 v19, v19, v7
	s_waitcnt vmcnt(9)
	v_add_u32_e32 v19, v19, v8
	s_waitcnt vmcnt(8)
	v_add_u32_e32 v19, v19, v9
	s_waitcnt vmcnt(7)
	v_add_u32_e32 v19, v19, v10
	s_waitcnt vmcnt(6)
	v_add_u32_e32 v19, v19, v11
	s_waitcnt vmcnt(5)
	v_add_u32_e32 v19, v19, v12
	s_waitcnt vmcnt(4)
	v_add_u32_e32 v19, v19, v13
	s_waitcnt vmcnt(3)
	v_add_u32_e32 v19, v19, v14
	s_waitcnt vmcnt(2)
	v_add_u32_e32 v19, v19, v15
	s_waitcnt vmcnt(1)
	v_add_u32_e32 v19, v19, v16
	s_waitcnt vmcnt(0)
	v_add_u32_e32 v19, v19, v17
	v_cmp_eq_u32_e32 vcc, s18, v19
	s_cbranch_vccnz .LBB0_94
	s_and_b32 s39, s38, 0xff
	s_cmp_eq_u32 s39, 0
	s_mov_b64 s[44:45], -1
	s_sleep 0
	s_cbranch_scc0 .LBB0_99
	global_load_dword v19, v3, s[50:51] sc1
	s_waitcnt vmcnt(0)
	v_cmp_eq_u32_e32 vcc, 0, v19
	s_cbranch_vccnz .LBB0_101
	s_mov_b64 s[44:45], 0

.LBB0_111:
	s_and_b32 s38, s18, 0xff
	s_mov_b64 s[54:55], -1
	s_cmp_lg_u32 s38, 0
	s_mov_b64 s[62:63], -1
	s_sleep 0
	s_cbranch_scc1 .LBB0_114
	global_load_dword v4, v3, s[50:51] sc1
	s_waitcnt vmcnt(0)
	v_cmp_eq_u32_e32 vcc, 0, v4
	s_cbranch_vccnz .LBB0_116
	s_mov_b64 s[62:63], 0
	s_mov_b64 s[56:57], -1

.LBB0_223:
	v_readlane_b32 s4, v250, 54
	v_readlane_b32 s5, v250, 55
	s_mov_b64 s[6:7], -1
	s_nop 3
	global_load_dword v1, v19, s[4:5] sc1
	v_readlane_b32 s4, v251, 18
	v_readlane_b32 s5, v251, 19
	s_nop 4
	global_load_dword v2, v19, s[4:5] sc1
	v_readlane_b32 s4, v251, 27
	v_readlane_b32 s5, v251, 28
	s_waitcnt vmcnt(0)
	v_add_u32_e32 v17, v2, v1
	s_nop 2
	global_load_dword v3, v19, s[4:5] sc1
	v_readlane_b32 s4, v251, 29
	v_readlane_b32 s5, v251, 30
	s_waitcnt vmcnt(0)
	v_add_u32_e32 v17, v17, v3
	s_nop 2
	global_load_dword v4, v19, s[4:5] sc1
	v_readlane_b32 s4, v251, 31
	v_readlane_b32 s5, v251, 32
	s_waitcnt vmcnt(0)
	v_add_u32_e32 v17, v17, v4
	s_nop 2
	global_load_dword v5, v19, s[4:5] sc1
	v_readlane_b32 s4, v251, 33
	v_readlane_b32 s5, v251, 34
	s_waitcnt vmcnt(0)
	v_add_u32_e32 v17, v17, v5
	s_nop 2
	global_load_dword v6, v19, s[4:5] sc1
	v_readlane_b32 s4, v251, 35
	v_readlane_b32 s5, v251, 36
	s_waitcnt vmcnt(0)
	v_add_u32_e32 v17, v17, v6
	s_nop 2
	global_load_dword v7, v19, s[4:5] sc1
	v_readlane_b32 s4, v251, 37
	v_readlane_b32 s5, v251, 38
	s_waitcnt vmcnt(0)
	v_add_u32_e32 v17, v17, v7
	s_nop 2
	global_load_dword v8, v19, s[4:5] sc1
	v_readlane_b32 s4, v251, 39
	v_readlane_b32 s5, v251, 40
	s_waitcnt vmcnt(0)
	v_add_u32_e32 v17, v17, v8
	s_nop 2
	global_load_dword v9, v19, s[4:5] sc1
	v_readlane_b32 s4, v251, 41
	v_readlane_b32 s5, v251, 42
	s_waitcnt vmcnt(0)
	v_add_u32_e32 v17, v17, v9
	s_nop 2
	global_load_dword v10, v19, s[4:5] sc1
	v_readlane_b32 s4, v251, 43
	v_readlane_b32 s5, v251, 44
	s_waitcnt vmcnt(0)
	v_add_u32_e32 v17, v17, v10
	s_nop 2
	global_load_dword v11, v19, s[4:5] sc1
	v_readlane_b32 s4, v251, 45
	v_readlane_b32 s5, v251, 46
	s_waitcnt vmcnt(0)
	v_add_u32_e32 v17, v17, v11
	s_nop 2
	global_load_dword v12, v19, s[4:5] sc1
	v_readlane_b32 s4, v251, 47
	v_readlane_b32 s5, v251, 48
	s_waitcnt vmcnt(0)
	v_add_u32_e32 v17, v17, v12
	s_nop 2
	global_load_dword v13, v19, s[4:5] sc1
	v_readlane_b32 s4, v251, 49
	v_readlane_b32 s5, v251, 50
	s_waitcnt vmcnt(0)
	v_add_u32_e32 v17, v17, v13
	s_nop 2
	global_load_dword v14, v19, s[4:5] sc1
	v_readlane_b32 s4, v251, 51
	v_readlane_b32 s5, v251, 52
	s_waitcnt vmcnt(0)
	v_add_u32_e32 v17, v17, v14
	s_nop 2
	global_load_dword v15, v19, s[4:5] sc1
	v_readlane_b32 s4, v251, 53
	v_readlane_b32 s5, v251, 54
	s_waitcnt vmcnt(0)
	v_add_u32_e32 v17, v17, v15
	s_nop 2
	global_load_dword v16, v19, s[4:5] sc1
	s_mov_b64 s[4:5], -1
	s_waitcnt vmcnt(0)
	v_add_u32_e32 v17, v17, v16
	v_cmp_eq_u32_e32 vcc, s10, v17
	s_cbranch_vccnz .LBB0_222
	s_and_b32 s4, s11, 0xff
	s_cmp_eq_u32 s4, 0
	s_mov_b64 s[4:5], -1
	s_mov_b64 s[8:9], -1
	s_sleep 0
	s_cbranch_scc0 .LBB0_227
	v_readlane_b32 s4, v251, 25
	v_readlane_b32 s5, v251, 26
	s_nop 4
	global_load_dword v17, v19, s[4:5] sc1
	s_waitcnt vmcnt(0)
	v_cmp_eq_u32_e32 vcc, 0, v17
	s_cbranch_vccnz .LBB0_229
	s_mov_b64 s[8:9], 0
	s_mov_b64 s[4:5], -1

.LBB0_239:
	s_and_b32 s14, s18, 0xff
	s_mov_b64 s[12:13], -1
	s_cmp_lg_u32 s14, 0
	s_mov_b64 s[16:17], -1
	s_sleep 0
	s_cbranch_scc1 .LBB0_242
	v_readlane_b32 s14, v251, 25
	v_readlane_b32 s15, v251, 26
	s_nop 4
	global_load_dword v2, v19, s[14:15] sc1
	s_waitcnt vmcnt(0)
	v_cmp_eq_u32_e32 vcc, 0, v2
	s_cbranch_vccnz .LBB0_244
	s_mov_b64 s[16:17], 0
	s_mov_b64 s[14:15], -1

.LBB0_340:
	v_readlane_b32 s14, v250, 54
	v_readlane_b32 s15, v250, 55
	s_mov_b64 s[16:17], -1
	s_nop 3
	global_load_dword v1, v19, s[14:15] sc1
	v_readlane_b32 s14, v251, 18
	v_readlane_b32 s15, v251, 19
	s_nop 4
	global_load_dword v2, v19, s[14:15] sc1
	v_readlane_b32 s14, v251, 27
	v_readlane_b32 s15, v251, 28
	s_waitcnt vmcnt(0)
	v_add_u32_e32 v17, v2, v1
	s_nop 2
	global_load_dword v3, v19, s[14:15] sc1
	v_readlane_b32 s14, v251, 29
	v_readlane_b32 s15, v251, 30
	s_waitcnt vmcnt(0)
	v_add_u32_e32 v17, v17, v3
	s_nop 2
	global_load_dword v4, v19, s[14:15] sc1
	v_readlane_b32 s14, v251, 31
	v_readlane_b32 s15, v251, 32
	s_waitcnt vmcnt(0)
	v_add_u32_e32 v17, v17, v4
	s_nop 2
	global_load_dword v5, v19, s[14:15] sc1
	v_readlane_b32 s14, v251, 33
	v_readlane_b32 s15, v251, 34
	s_waitcnt vmcnt(0)
	v_add_u32_e32 v17, v17, v5
	s_nop 2
	global_load_dword v6, v19, s[14:15] sc1
	v_readlane_b32 s14, v251, 35
	v_readlane_b32 s15, v251, 36
	s_waitcnt vmcnt(0)
	v_add_u32_e32 v17, v17, v6
	s_nop 2
	global_load_dword v7, v19, s[14:15] sc1
	v_readlane_b32 s14, v251, 37
	v_readlane_b32 s15, v251, 38
	s_waitcnt vmcnt(0)
	v_add_u32_e32 v17, v17, v7
	s_nop 2
	global_load_dword v8, v19, s[14:15] sc1
	v_readlane_b32 s14, v251, 39
	v_readlane_b32 s15, v251, 40
	s_waitcnt vmcnt(0)
	v_add_u32_e32 v17, v17, v8
	s_nop 2
	global_load_dword v9, v19, s[14:15] sc1
	v_readlane_b32 s14, v251, 41
	v_readlane_b32 s15, v251, 42
	s_waitcnt vmcnt(0)
	v_add_u32_e32 v17, v17, v9
	s_nop 2
	global_load_dword v10, v19, s[14:15] sc1
	v_readlane_b32 s14, v251, 43
	v_readlane_b32 s15, v251, 44
	s_waitcnt vmcnt(0)
	v_add_u32_e32 v17, v17, v10
	s_nop 2
	global_load_dword v11, v19, s[14:15] sc1
	v_readlane_b32 s14, v251, 45
	v_readlane_b32 s15, v251, 46
	s_waitcnt vmcnt(0)
	v_add_u32_e32 v17, v17, v11
	s_nop 2
	global_load_dword v12, v19, s[14:15] sc1
	v_readlane_b32 s14, v251, 47
	v_readlane_b32 s15, v251, 48
	s_waitcnt vmcnt(0)
	v_add_u32_e32 v17, v17, v12
	s_nop 2
	global_load_dword v13, v19, s[14:15] sc1
	v_readlane_b32 s14, v251, 49
	v_readlane_b32 s15, v251, 50
	s_waitcnt vmcnt(0)
	v_add_u32_e32 v17, v17, v13
	s_nop 2
	global_load_dword v14, v19, s[14:15] sc1
	v_readlane_b32 s14, v251, 51
	v_readlane_b32 s15, v251, 52
	s_waitcnt vmcnt(0)
	v_add_u32_e32 v17, v17, v14
	s_nop 2
	global_load_dword v15, v19, s[14:15] sc1
	v_readlane_b32 s14, v251, 53
	v_readlane_b32 s15, v251, 54
	s_waitcnt vmcnt(0)
	v_add_u32_e32 v17, v17, v15
	s_nop 2
	global_load_dword v16, v19, s[14:15] sc1
	s_mov_b64 s[14:15], -1
	s_waitcnt vmcnt(0)
	v_add_u32_e32 v17, v17, v16
	v_cmp_eq_u32_e32 vcc, s20, v17
	s_cbranch_vccnz .LBB0_339
	s_and_b32 s14, s21, 0xff
	s_cmp_eq_u32 s14, 0
	s_mov_b64 s[14:15], -1
	s_mov_b64 s[18:19], -1
	s_sleep 0
	s_cbranch_scc0 .LBB0_344
	v_readlane_b32 s14, v251, 25
	v_readlane_b32 s15, v251, 26
	s_nop 4
	global_load_dword v17, v19, s[14:15] sc1
	s_waitcnt vmcnt(0)
	v_cmp_eq_u32_e32 vcc, 0, v17
	s_cbranch_vccnz .LBB0_346
	s_mov_b64 s[18:19], 0
	s_mov_b64 s[14:15], -1

.LBB0_356:
	s_and_b32 s24, s38, 0xff
	s_mov_b64 s[22:23], -1
	s_cmp_lg_u32 s24, 0
	s_mov_b64 s[26:27], -1
	s_sleep 0
	s_cbranch_scc1 .LBB0_359
	v_readlane_b32 s24, v251, 25
	v_readlane_b32 s25, v251, 26
	s_nop 4
	global_load_dword v2, v19, s[24:25] sc1
	s_waitcnt vmcnt(0)
	v_cmp_eq_u32_e32 vcc, 0, v2
	s_cbranch_vccnz .LBB0_361
	s_mov_b64 s[26:27], 0
	s_mov_b64 s[24:25], -1

.LBB0_1623:
	s_and_b32 s14, s19, 0xff
	s_mov_b64 s[12:13], -1
	s_cmp_lg_u32 s14, 0
	s_mov_b64 s[16:17], -1
	s_sleep 0
	s_cbranch_scc1 .LBB0_1626
	v_readlane_b32 s14, v251, 25
	v_readlane_b32 s15, v251, 26
	s_nop 4
	global_load_dword v2, v19, s[14:15] sc1
	s_waitcnt vmcnt(0)
	v_cmp_eq_u32_e32 vcc, 0, v2
	s_cbranch_vccnz .LBB0_1628
	s_mov_b64 s[16:17], 0
	s_mov_b64 s[14:15], -1

.LBB0_1794:
	v_readlane_b32 s8, v250, 54
	v_readlane_b32 s9, v250, 55
	s_mov_b64 s[10:11], -1
	s_nop 3
	global_load_dword v1, v19, s[8:9] sc1
	v_readlane_b32 s8, v251, 18
	v_readlane_b32 s9, v251, 19
	s_nop 4
	global_load_dword v2, v19, s[8:9] sc1
	v_readlane_b32 s8, v251, 27
	v_readlane_b32 s9, v251, 28
	s_waitcnt vmcnt(0)
	v_add_u32_e32 v17, v2, v1
	s_nop 2
	global_load_dword v3, v19, s[8:9] sc1
	v_readlane_b32 s8, v251, 29
	v_readlane_b32 s9, v251, 30
	s_waitcnt vmcnt(0)
	v_add_u32_e32 v17, v17, v3
	s_nop 2
	global_load_dword v4, v19, s[8:9] sc1
	v_readlane_b32 s8, v251, 31
	v_readlane_b32 s9, v251, 32
	s_waitcnt vmcnt(0)
	v_add_u32_e32 v17, v17, v4
	s_nop 2
	global_load_dword v5, v19, s[8:9] sc1
	v_readlane_b32 s8, v251, 33
	v_readlane_b32 s9, v251, 34
	s_waitcnt vmcnt(0)
	v_add_u32_e32 v17, v17, v5
	s_nop 2
	global_load_dword v6, v19, s[8:9] sc1
	v_readlane_b32 s8, v251, 35
	v_readlane_b32 s9, v251, 36
	s_waitcnt vmcnt(0)
	v_add_u32_e32 v17, v17, v6
	s_nop 2
	global_load_dword v7, v19, s[8:9] sc1
	v_readlane_b32 s8, v251, 37
	v_readlane_b32 s9, v251, 38
	s_waitcnt vmcnt(0)
	v_add_u32_e32 v17, v17, v7
	s_nop 2
	global_load_dword v8, v19, s[8:9] sc1
	v_readlane_b32 s8, v251, 39
	v_readlane_b32 s9, v251, 40
	s_waitcnt vmcnt(0)
	v_add_u32_e32 v17, v17, v8
	s_nop 2
	global_load_dword v9, v19, s[8:9] sc1
	v_readlane_b32 s8, v251, 41
	v_readlane_b32 s9, v251, 42
	s_waitcnt vmcnt(0)
	v_add_u32_e32 v17, v17, v9
	s_nop 2
	global_load_dword v10, v19, s[8:9] sc1
	v_readlane_b32 s8, v251, 43
	v_readlane_b32 s9, v251, 44
	s_waitcnt vmcnt(0)
	v_add_u32_e32 v17, v17, v10
	s_nop 2
	global_load_dword v11, v19, s[8:9] sc1
	v_readlane_b32 s8, v251, 45
	v_readlane_b32 s9, v251, 46
	s_waitcnt vmcnt(0)
	v_add_u32_e32 v17, v17, v11
	s_nop 2
	global_load_dword v12, v19, s[8:9] sc1
	v_readlane_b32 s8, v251, 47
	v_readlane_b32 s9, v251, 48
	s_waitcnt vmcnt(0)
	v_add_u32_e32 v17, v17, v12
	s_nop 2
	global_load_dword v13, v19, s[8:9] sc1
	v_readlane_b32 s8, v251, 49
	v_readlane_b32 s9, v251, 50
	s_waitcnt vmcnt(0)
	v_add_u32_e32 v17, v17, v13
	s_nop 2
	global_load_dword v14, v19, s[8:9] sc1
	v_readlane_b32 s8, v251, 51
	v_readlane_b32 s9, v251, 52
	s_waitcnt vmcnt(0)
	v_add_u32_e32 v17, v17, v14
	s_nop 2
	global_load_dword v15, v19, s[8:9] sc1
	v_readlane_b32 s8, v251, 53
	v_readlane_b32 s9, v251, 54
	s_waitcnt vmcnt(0)
	v_add_u32_e32 v17, v17, v15
	s_nop 2
	global_load_dword v16, v19, s[8:9] sc1
	s_mov_b64 s[8:9], -1
	s_waitcnt vmcnt(0)
	v_add_u32_e32 v17, v17, v16
	v_cmp_eq_u32_e32 vcc, s14, v17
	s_cbranch_vccnz .LBB0_1793
	s_and_b32 s8, s15, 0xff
	s_cmp_eq_u32 s8, 0
	s_mov_b64 s[8:9], -1
	s_mov_b64 s[12:13], -1
	s_sleep 0
	s_cbranch_scc0 .LBB0_1798
	v_readlane_b32 s8, v251, 25
	v_readlane_b32 s9, v251, 26
	s_nop 4
	global_load_dword v17, v19, s[8:9] sc1
	s_waitcnt vmcnt(0)
	v_cmp_eq_u32_e32 vcc, 0, v17
	s_cbranch_vccnz .LBB0_1800
	s_mov_b64 s[12:13], 0
	s_mov_b64 s[8:9], -1

.LBB0_1810:
	s_and_b32 s18, s22, 0xff
	s_mov_b64 s[16:17], -1
	s_cmp_lg_u32 s18, 0
	s_mov_b64 s[20:21], -1
	s_sleep 0
	s_cbranch_scc1 .LBB0_1813
	v_readlane_b32 s18, v251, 25
	v_readlane_b32 s19, v251, 26
	s_nop 4
	global_load_dword v2, v19, s[18:19] sc1
	s_waitcnt vmcnt(0)
	v_cmp_eq_u32_e32 vcc, 0, v2
	s_cbranch_vccnz .LBB0_1815
	s_mov_b64 s[20:21], 0
	s_mov_b64 s[18:19], -1
